# in-projection and FFN-in K-loops rotated: taken back edge at the end of the light load slot before a barrier
# baseline (speedup 1.0000x reference)
.Lrot1_R:
	s_barrier
	s_waitcnt lgkmcnt(0)
	v_mfma_f32_16x16x32_bf16 v[80:83], v[52:55], v[208:211], v[80:83]
	v_mfma_f32_16x16x32_bf16 v[76:79], v[68:71], v[208:211], v[76:79]
	v_mfma_f32_16x16x32_bf16 v[64:67], v[52:55], v[216:219], v[64:67]
	v_mfma_f32_16x16x32_bf16 v[60:63], v[68:71], v[216:219], v[60:63]
	v_mfma_f32_16x16x32_bf16 v[48:51], v[52:55], v[224:227], v[48:51]
	v_mfma_f32_16x16x32_bf16 v[44:47], v[68:71], v[224:227], v[44:47]
	v_mfma_f32_16x16x32_bf16 v[16:19], v[52:55], v[232:235], v[16:19]
	v_mfma_f32_16x16x32_bf16 v[12:15], v[68:71], v[232:235], v[12:15]
	v_mfma_f32_16x16x32_bf16 v[80:83], v[56:59], v[212:215], v[80:83]
	v_mfma_f32_16x16x32_bf16 v[76:79], v[72:75], v[212:215], v[76:79]
	v_mfma_f32_16x16x32_bf16 v[64:67], v[56:59], v[220:223], v[64:67]
	v_mfma_f32_16x16x32_bf16 v[60:63], v[72:75], v[220:223], v[60:63]
	v_mfma_f32_16x16x32_bf16 v[48:51], v[56:59], v[228:231], v[48:51]
	v_mfma_f32_16x16x32_bf16 v[44:47], v[72:75], v[228:231], v[44:47]
	v_mfma_f32_16x16x32_bf16 v[16:19], v[56:59], v[236:239], v[16:19]
	v_mfma_f32_16x16x32_bf16 v[12:15], v[72:75], v[236:239], v[12:15]
	v_mfma_f32_16x16x32_bf16 v[20:23], v[158:161], v[208:211], v[20:23]
	v_mfma_f32_16x16x32_bf16 v[72:75], v[162:165], v[212:215], v[20:23]
	v_mfma_f32_16x16x32_bf16 v[20:23], v[174:177], v[208:211], v[24:27]
	v_mfma_f32_16x16x32_bf16 v[68:71], v[178:181], v[212:215], v[20:23]
	v_mfma_f32_16x16x32_bf16 v[20:23], v[158:161], v[216:219], v[28:31]
	v_mfma_f32_16x16x32_bf16 v[56:59], v[162:165], v[220:223], v[20:23]
	v_mfma_f32_16x16x32_bf16 v[20:23], v[174:177], v[216:219], v[36:39]
	v_mfma_f32_16x16x32_bf16 v[52:55], v[178:181], v[220:223], v[20:23]
	v_mfma_f32_16x16x32_bf16 v[20:23], v[158:161], v[224:227], v[40:43]
	v_mfma_f32_16x16x32_bf16 v[40:43], v[162:165], v[228:231], v[20:23]
	v_mfma_f32_16x16x32_bf16 v[20:23], v[174:177], v[224:227], v[32:35]
	v_mfma_f32_16x16x32_bf16 v[8:11], v[158:161], v[232:235], v[8:11]
	v_mfma_f32_16x16x32_bf16 v[4:7], v[174:177], v[232:235], v[4:7]
	v_mfma_f32_16x16x32_bf16 v[32:35], v[178:181], v[228:231], v[20:23]
	v_mfma_f32_16x16x32_bf16 v[8:11], v[162:165], v[236:239], v[8:11]
	v_mfma_f32_16x16x32_bf16 v[4:7], v[178:181], v[236:239], v[4:7]
	s_barrier
	s_add_i32 vcc_hi, vcc_hi, 2
	s_add_u32 s18, s18, 0x100
	s_addc_u32 s19, s19, 0
	s_add_u32 s71, s71, 0x100
	s_addc_u32 vcc_lo, vcc_lo, 0
	s_cmp_gt_u32 vcc_hi, 13
	s_cbranch_scc1 .Lrot1_X
.LBB0_233:
	s_add_u32 s6, s18, 0xfffc0080
	s_addc_u32 s33, s19, -1
	s_add_i32 s94, 0, 0x10000
	s_cmp_eq_u32 vcc_hi, 12
	s_cselect_b32 s79, s15, s33
	s_cselect_b32 s78, s17, s6
	s_cselect_b32 s77, s24, vcc_lo
	s_cselect_b32 s76, s69, s71
	s_add_i32 s6, 0, 0x14000
	v_add_u32_e32 v36, s94, v184
	v_add_u32_e32 v168, s6, v184
	ds_read_b128 v[20:23], v36
	ds_read_b128 v[24:27], v36 offset:1024
	ds_read_b128 v[28:31], v36 offset:2048
	ds_read_b128 v[36:39], v36 offset:3072
	ds_read_b128 v[158:161], v168
	ds_read_b128 v[162:165], v168 offset:1024
	ds_read_b128 v[174:177], v168 offset:2048
	ds_read_b128 v[178:181], v168 offset:3072
	v_lshl_add_u64 v[168:169], s[18:19], 0, v[154:155]
	s_add_i32 m0, s35, 0xc000
	ds_read_b128 v[208:211], v206
	ds_read_b128 v[212:215], v206 offset:1024
	ds_read_b128 v[216:219], v206 offset:2048
	ds_read_b128 v[220:223], v206 offset:3072
	ds_read_b128 v[224:227], v206 offset:4096
	ds_read_b128 v[228:231], v206 offset:5120
	ds_read_b128 v[232:235], v206 offset:6144
	ds_read_b128 v[236:239], v206 offset:7168
	global_load_lds_dwordx4 v[168:169], off
	v_lshl_add_u64 v[168:169], s[18:19], 0, v[156:157]
	s_add_i32 m0, s35, 0xe000
	s_nop 0
	global_load_lds_dwordx4 v[168:169], off
	s_waitcnt vmcnt(8)
	s_waitcnt lgkmcnt(0)
	s_barrier
	s_waitcnt lgkmcnt(0)
	v_mfma_f32_16x16x32_bf16 v[144:147], v[20:23], v[208:211], v[144:147]
	v_mfma_f32_16x16x32_bf16 v[140:143], v[28:31], v[208:211], v[140:143]
	v_mfma_f32_16x16x32_bf16 v[128:131], v[20:23], v[216:219], v[128:131]
	v_mfma_f32_16x16x32_bf16 v[124:127], v[28:31], v[216:219], v[124:127]
	v_mfma_f32_16x16x32_bf16 v[112:115], v[20:23], v[224:227], v[112:115]
	v_mfma_f32_16x16x32_bf16 v[108:111], v[28:31], v[224:227], v[108:111]
	v_mfma_f32_16x16x32_bf16 v[96:99], v[20:23], v[232:235], v[96:99]
	v_mfma_f32_16x16x32_bf16 v[92:95], v[28:31], v[232:235], v[92:95]
	v_mfma_f32_16x16x32_bf16 v[144:147], v[24:27], v[212:215], v[144:147]
	v_mfma_f32_16x16x32_bf16 v[140:143], v[36:39], v[212:215], v[140:143]
	v_mfma_f32_16x16x32_bf16 v[128:131], v[24:27], v[220:223], v[128:131]
	v_mfma_f32_16x16x32_bf16 v[124:127], v[36:39], v[220:223], v[124:127]
	v_mfma_f32_16x16x32_bf16 v[112:115], v[24:27], v[228:231], v[112:115]
	v_mfma_f32_16x16x32_bf16 v[108:111], v[36:39], v[228:231], v[108:111]
	v_mfma_f32_16x16x32_bf16 v[96:99], v[24:27], v[236:239], v[96:99]
	v_mfma_f32_16x16x32_bf16 v[92:95], v[36:39], v[236:239], v[92:95]
	v_mfma_f32_16x16x32_bf16 v[136:139], v[158:161], v[208:211], v[136:139]
	v_mfma_f32_16x16x32_bf16 v[132:135], v[174:177], v[208:211], v[132:135]
	v_mfma_f32_16x16x32_bf16 v[120:123], v[158:161], v[216:219], v[120:123]
	v_mfma_f32_16x16x32_bf16 v[116:119], v[174:177], v[216:219], v[116:119]
	v_mfma_f32_16x16x32_bf16 v[104:107], v[158:161], v[224:227], v[104:107]
	v_mfma_f32_16x16x32_bf16 v[100:103], v[174:177], v[224:227], v[100:103]
	v_mfma_f32_16x16x32_bf16 v[88:91], v[158:161], v[232:235], v[88:91]
	v_mfma_f32_16x16x32_bf16 v[84:87], v[174:177], v[232:235], v[84:87]
	v_mfma_f32_16x16x32_bf16 v[136:139], v[162:165], v[212:215], v[136:139]
	v_mfma_f32_16x16x32_bf16 v[132:135], v[178:181], v[212:215], v[132:135]
	v_mfma_f32_16x16x32_bf16 v[120:123], v[162:165], v[220:223], v[120:123]
	v_mfma_f32_16x16x32_bf16 v[116:119], v[178:181], v[220:223], v[116:119]
	v_mfma_f32_16x16x32_bf16 v[104:107], v[162:165], v[228:231], v[104:107]
	v_mfma_f32_16x16x32_bf16 v[100:103], v[178:181], v[228:231], v[100:103]
	v_mfma_f32_16x16x32_bf16 v[88:91], v[162:165], v[236:239], v[88:91]
	v_mfma_f32_16x16x32_bf16 v[84:87], v[178:181], v[236:239], v[84:87]
	s_barrier
	s_add_i32 s33, s94, s57
	v_lshl_add_u64 v[168:169], s[76:77], 0, v[2:3]
	s_mov_b32 m0, s33
	ds_read_b128 v[208:211], v206 offset:16384
	ds_read_b128 v[212:215], v206 offset:17408
	ds_read_b128 v[216:219], v206 offset:18432
	ds_read_b128 v[220:223], v206 offset:19456
	ds_read_b128 v[224:227], v206 offset:20480
	ds_read_b128 v[228:231], v206 offset:21504
	ds_read_b128 v[232:235], v206 offset:22528
	ds_read_b128 v[236:239], v206 offset:23552
	global_load_lds_dwordx4 v[168:169], off
	s_add_i32 m0, s33, 0x2000
	s_add_u32 s94, s76, 0x40000
	v_lshl_add_u64 v[170:171], s[76:77], 0, v[152:153]
	s_addc_u32 s95, s77, 0
	s_add_i32 s6, s6, s57
	global_load_lds_dwordx4 v[170:171], off
	v_lshl_add_u64 v[182:183], s[94:95], 0, v[2:3]
	s_mov_b32 m0, s6
	v_lshl_add_u64 v[240:241], s[78:79], 0, v[150:151]
	global_load_lds_dwordx4 v[182:183], off
	v_lshl_add_u64 v[182:183], s[94:95], 0, v[152:153]
	s_add_i32 m0, s6, 0x2000
	s_nop 0
	global_load_lds_dwordx4 v[182:183], off
	v_lshl_add_u64 v[182:183], s[78:79], 0, v[148:149]
	s_mov_b32 m0, s35
	s_nop 0
	global_load_lds_dwordx4 v[182:183], off
	s_mov_b32 m0, s9
	s_nop 0
	global_load_lds_dwordx4 v[240:241], off
	s_waitcnt vmcnt(8)
	s_waitcnt lgkmcnt(0)
	s_barrier
	s_waitcnt lgkmcnt(0)
	v_mfma_f32_16x16x32_bf16 v[80:83], v[20:23], v[208:211], v[80:83]
	v_mfma_f32_16x16x32_bf16 v[76:79], v[28:31], v[208:211], v[76:79]
	v_mfma_f32_16x16x32_bf16 v[64:67], v[20:23], v[216:219], v[64:67]
	v_mfma_f32_16x16x32_bf16 v[60:63], v[28:31], v[216:219], v[60:63]
	v_mfma_f32_16x16x32_bf16 v[48:51], v[20:23], v[224:227], v[48:51]
	v_mfma_f32_16x16x32_bf16 v[44:47], v[28:31], v[224:227], v[44:47]
	v_mfma_f32_16x16x32_bf16 v[16:19], v[20:23], v[232:235], v[16:19]
	v_mfma_f32_16x16x32_bf16 v[12:15], v[28:31], v[232:235], v[12:15]
	v_mfma_f32_16x16x32_bf16 v[80:83], v[24:27], v[212:215], v[80:83]
	v_mfma_f32_16x16x32_bf16 v[76:79], v[36:39], v[212:215], v[76:79]
	v_mfma_f32_16x16x32_bf16 v[64:67], v[24:27], v[220:223], v[64:67]
	v_mfma_f32_16x16x32_bf16 v[60:63], v[36:39], v[220:223], v[60:63]
	v_mfma_f32_16x16x32_bf16 v[48:51], v[24:27], v[228:231], v[48:51]
	v_mfma_f32_16x16x32_bf16 v[44:47], v[36:39], v[228:231], v[44:47]
	v_mfma_f32_16x16x32_bf16 v[16:19], v[24:27], v[236:239], v[16:19]
	v_mfma_f32_16x16x32_bf16 v[12:15], v[36:39], v[236:239], v[12:15]
	v_mfma_f32_16x16x32_bf16 v[40:43], v[158:161], v[224:227], v[40:43]
	v_mfma_f32_16x16x32_bf16 v[32:35], v[174:177], v[224:227], v[32:35]
	v_mfma_f32_16x16x32_bf16 v[8:11], v[158:161], v[232:235], v[8:11]
	v_mfma_f32_16x16x32_bf16 v[4:7], v[174:177], v[232:235], v[4:7]
	v_mfma_f32_16x16x32_bf16 v[20:23], v[158:161], v[208:211], v[72:75]
	v_mfma_f32_16x16x32_bf16 v[24:27], v[174:177], v[208:211], v[68:71]
	v_mfma_f32_16x16x32_bf16 v[28:31], v[158:161], v[216:219], v[56:59]
	v_mfma_f32_16x16x32_bf16 v[36:39], v[174:177], v[216:219], v[52:55]
	v_mfma_f32_16x16x32_bf16 v[40:43], v[162:165], v[228:231], v[40:43]
	v_mfma_f32_16x16x32_bf16 v[32:35], v[178:181], v[228:231], v[32:35]
	v_mfma_f32_16x16x32_bf16 v[8:11], v[162:165], v[236:239], v[8:11]
	v_mfma_f32_16x16x32_bf16 v[4:7], v[178:181], v[236:239], v[4:7]
	v_mfma_f32_16x16x32_bf16 v[20:23], v[162:165], v[212:215], v[20:23]
	v_mfma_f32_16x16x32_bf16 v[24:27], v[178:181], v[212:215], v[24:27]
	v_mfma_f32_16x16x32_bf16 v[28:31], v[162:165], v[220:223], v[28:31]
	v_mfma_f32_16x16x32_bf16 v[36:39], v[178:181], v[220:223], v[36:39]
	s_barrier
	s_add_i32 s6, 0, 0x18000
	s_add_i32 s33, 0, 0x1c000
	v_add_u32_e32 v72, s6, v184
	v_add_u32_e32 v178, s33, v184
	ds_read_b128 v[52:55], v72
	ds_read_b128 v[56:59], v72 offset:1024
	ds_read_b128 v[68:71], v72 offset:2048
	ds_read_b128 v[72:75], v72 offset:3072
	ds_read_b128 v[158:161], v178
	ds_read_b128 v[162:165], v178 offset:1024
	ds_read_b128 v[174:177], v178 offset:2048
	ds_read_b128 v[178:181], v178 offset:3072
	s_add_u32 s78, s78, 0x40000
	s_addc_u32 s79, s79, 0
	s_mov_b32 m0, s4
	v_lshl_add_u64 v[242:243], s[78:79], 0, v[148:149]
	ds_read_b128 v[208:211], v206 offset:32768
	ds_read_b128 v[212:215], v206 offset:33792
	ds_read_b128 v[216:219], v206 offset:34816
	ds_read_b128 v[220:223], v206 offset:35840
	ds_read_b128 v[224:227], v206 offset:36864
	ds_read_b128 v[228:231], v206 offset:37888
	ds_read_b128 v[232:235], v206 offset:38912
	ds_read_b128 v[236:239], v206 offset:39936
	global_load_lds_dwordx4 v[242:243], off
	v_lshl_add_u64 v[242:243], s[78:79], 0, v[150:151]
	s_mov_b32 m0, s20
	s_nop 0
	global_load_lds_dwordx4 v[242:243], off
	s_waitcnt vmcnt(8)
	s_waitcnt lgkmcnt(0)
	s_barrier
	s_waitcnt lgkmcnt(0)
	v_mfma_f32_16x16x32_bf16 v[144:147], v[52:55], v[208:211], v[144:147]
	v_mfma_f32_16x16x32_bf16 v[140:143], v[68:71], v[208:211], v[140:143]
	v_mfma_f32_16x16x32_bf16 v[128:131], v[52:55], v[216:219], v[128:131]
	v_mfma_f32_16x16x32_bf16 v[124:127], v[68:71], v[216:219], v[124:127]
	v_mfma_f32_16x16x32_bf16 v[112:115], v[52:55], v[224:227], v[112:115]
	v_mfma_f32_16x16x32_bf16 v[108:111], v[68:71], v[224:227], v[108:111]
	v_mfma_f32_16x16x32_bf16 v[96:99], v[52:55], v[232:235], v[96:99]
	v_mfma_f32_16x16x32_bf16 v[92:95], v[68:71], v[232:235], v[92:95]
	v_mfma_f32_16x16x32_bf16 v[144:147], v[56:59], v[212:215], v[144:147]
	v_mfma_f32_16x16x32_bf16 v[140:143], v[72:75], v[212:215], v[140:143]
	v_mfma_f32_16x16x32_bf16 v[128:131], v[56:59], v[220:223], v[128:131]
	v_mfma_f32_16x16x32_bf16 v[124:127], v[72:75], v[220:223], v[124:127]
	v_mfma_f32_16x16x32_bf16 v[112:115], v[56:59], v[228:231], v[112:115]
	v_mfma_f32_16x16x32_bf16 v[108:111], v[72:75], v[228:231], v[108:111]
	v_mfma_f32_16x16x32_bf16 v[96:99], v[56:59], v[236:239], v[96:99]
	v_mfma_f32_16x16x32_bf16 v[92:95], v[72:75], v[236:239], v[92:95]
	v_mfma_f32_16x16x32_bf16 v[136:139], v[158:161], v[208:211], v[136:139]
	v_mfma_f32_16x16x32_bf16 v[132:135], v[174:177], v[208:211], v[132:135]
	v_mfma_f32_16x16x32_bf16 v[120:123], v[158:161], v[216:219], v[120:123]
	v_mfma_f32_16x16x32_bf16 v[116:119], v[174:177], v[216:219], v[116:119]
	v_mfma_f32_16x16x32_bf16 v[104:107], v[158:161], v[224:227], v[104:107]
	v_mfma_f32_16x16x32_bf16 v[100:103], v[174:177], v[224:227], v[100:103]
	v_mfma_f32_16x16x32_bf16 v[88:91], v[158:161], v[232:235], v[88:91]
	v_mfma_f32_16x16x32_bf16 v[84:87], v[174:177], v[232:235], v[84:87]
	v_mfma_f32_16x16x32_bf16 v[136:139], v[162:165], v[212:215], v[136:139]
	v_mfma_f32_16x16x32_bf16 v[132:135], v[178:181], v[212:215], v[132:135]
	v_mfma_f32_16x16x32_bf16 v[120:123], v[162:165], v[220:223], v[120:123]
	v_mfma_f32_16x16x32_bf16 v[116:119], v[178:181], v[220:223], v[116:119]
	v_mfma_f32_16x16x32_bf16 v[104:107], v[162:165], v[228:231], v[104:107]
	v_mfma_f32_16x16x32_bf16 v[100:103], v[178:181], v[228:231], v[100:103]
	v_mfma_f32_16x16x32_bf16 v[88:91], v[162:165], v[236:239], v[88:91]
	v_mfma_f32_16x16x32_bf16 v[84:87], v[178:181], v[236:239], v[84:87]
	s_barrier
	s_add_i32 s6, s6, s57
	v_lshl_add_u64 v[168:169], v[168:169], 0, s[30:31]
	s_mov_b32 m0, s6
	ds_read_b128 v[208:211], v206 offset:49152
	ds_read_b128 v[212:215], v206 offset:50176
	ds_read_b128 v[216:219], v206 offset:51200
	ds_read_b128 v[220:223], v206 offset:52224
	ds_read_b128 v[224:227], v206 offset:53248
	ds_read_b128 v[228:231], v206 offset:54272
	ds_read_b128 v[232:235], v206 offset:55296
	ds_read_b128 v[236:239], v206 offset:56320
	global_load_lds_dwordx4 v[168:169], off
	s_add_i32 m0, s6, 0x2000
	s_add_u32 s76, s76, 0x40080
	v_lshl_add_u64 v[168:169], v[170:171], 0, s[30:31]
	s_addc_u32 s77, s77, 0
	s_add_i32 s6, s33, s57
	global_load_lds_dwordx4 v[168:169], off
	v_lshl_add_u64 v[168:169], s[76:77], 0, v[2:3]
	s_mov_b32 m0, s6
	s_nop 0
	global_load_lds_dwordx4 v[168:169], off
	v_lshl_add_u64 v[168:169], s[76:77], 0, v[152:153]
	s_add_i32 m0, s6, 0x2000
	s_nop 0
	global_load_lds_dwordx4 v[168:169], off
	v_lshl_add_u64 v[168:169], v[182:183], 0, s[30:31]
	s_mov_b32 m0, s82
	s_nop 0
	global_load_lds_dwordx4 v[168:169], off
	v_lshl_add_u64 v[168:169], v[240:241], 0, s[30:31]
	s_mov_b32 m0, s27
	s_nop 0
	global_load_lds_dwordx4 v[168:169], off
	s_waitcnt vmcnt(8)
	s_waitcnt lgkmcnt(0)
	s_branch .Lrot1_R
.Lrot1_X:
	s_and_b64 vcc, exec, s[66:67]
	s_cbranch_vccz .LBB0_236
	s_barrier

.LBB0_663:
	s_ashr_i32 s61, s60, 31
	s_lshl_b64 s[10:11], s[60:61], 19
	s_add_u32 s62, s21, s10
	s_addc_u32 s63, s24, s11
	s_and_b64 s[10:11], s[12:13], exec
	s_cselect_b32 s10, s63, s69
	s_cselect_b32 s11, s62, s68
	s_ashr_i32 s59, s58, 31
	s_lshl_b64 s[64:65], s[58:59], 19
	s_add_u32 s64, s27, s64
	s_addc_u32 s65, s34, s65
	s_and_b64 s[72:73], s[12:13], exec
	s_cselect_b32 s15, s65, s71
	s_cselect_b32 s59, s64, s70
	s_add_u32 s68, s68, 0x40080
	s_addc_u32 s69, s69, 0
	s_add_u32 s61, s70, 0x100
	s_addc_u32 s67, s71, 0
	s_mov_b32 s80, -2
	s_add_u32 s6, s68, 0xfffc0080
	s_addc_u32 s33, s69, -1
	s_add_i32 s82, 0, 0x10000
	s_cmp_eq_u32 s80, 12
	s_cselect_b32 s73, s10, s33
	s_cselect_b32 s72, s11, s6
	v_add_u32_e32 v2, s82, v148
	s_cselect_b32 s71, s15, s67
	s_cselect_b32 s70, s59, s61
	s_add_i32 s6, 0, 0x14000
	ds_read_b128 v[152:155], v2
	ds_read_b128 v[156:159], v2 offset:1024
	ds_read_b128 v[160:163], v2 offset:2048
	ds_read_b128 v[168:171], v2 offset:3072
	v_add_u32_e32 v2, s6, v148
	ds_read_b128 v[174:177], v2
	ds_read_b128 v[178:181], v2 offset:1024
	ds_read_b128 v[182:185], v2 offset:2048
	ds_read_b128 v[186:189], v2 offset:3072
	v_lshl_add_u64 v[146:147], s[68:69], 0, v[142:143]
	s_add_i32 m0, s35, 0xc000
	ds_read_b128 v[200:203], v151
	ds_read_b128 v[204:207], v151 offset:1024
	ds_read_b128 v[208:211], v151 offset:2048
	ds_read_b128 v[212:215], v151 offset:3072
	ds_read_b128 v[216:219], v151 offset:4096
	ds_read_b128 v[220:223], v151 offset:5120
	ds_read_b128 v[224:227], v151 offset:6144
	ds_read_b128 v[228:231], v151 offset:7168
	global_load_lds_dwordx4 v[146:147], off
	v_lshl_add_u64 v[146:147], s[68:69], 0, v[144:145]
	s_add_i32 m0, s35, 0xe000
	s_nop 0
	global_load_lds_dwordx4 v[146:147], off
	s_waitcnt vmcnt(8)
	s_waitcnt lgkmcnt(0)
	s_barrier
	s_waitcnt lgkmcnt(0)
	v_mfma_f32_16x16x32_bf16 v[128:131], v[152:155], v[200:203], 0
	v_mfma_f32_16x16x32_bf16 v[120:123], v[160:163], v[200:203], 0
	v_mfma_f32_16x16x32_bf16 v[112:115], v[152:155], v[208:211], 0
	v_mfma_f32_16x16x32_bf16 v[104:107], v[160:163], v[208:211], 0
	v_mfma_f32_16x16x32_bf16 v[96:99], v[152:155], v[216:219], 0
	v_mfma_f32_16x16x32_bf16 v[88:91], v[160:163], v[216:219], 0
	v_mfma_f32_16x16x32_bf16 v[80:83], v[152:155], v[224:227], 0
	v_mfma_f32_16x16x32_bf16 v[72:75], v[160:163], v[224:227], 0
	v_mfma_f32_16x16x32_bf16 v[128:131], v[156:159], v[204:207], v[128:131]
	v_mfma_f32_16x16x32_bf16 v[120:123], v[168:171], v[204:207], v[120:123]
	v_mfma_f32_16x16x32_bf16 v[112:115], v[156:159], v[212:215], v[112:115]
	v_mfma_f32_16x16x32_bf16 v[104:107], v[168:171], v[212:215], v[104:107]
	v_mfma_f32_16x16x32_bf16 v[96:99], v[156:159], v[220:223], v[96:99]
	v_mfma_f32_16x16x32_bf16 v[88:91], v[168:171], v[220:223], v[88:91]
	v_mfma_f32_16x16x32_bf16 v[80:83], v[156:159], v[228:231], v[80:83]
	v_mfma_f32_16x16x32_bf16 v[72:75], v[168:171], v[228:231], v[72:75]
	v_mfma_f32_16x16x32_bf16 v[124:127], v[174:177], v[200:203], 0
	v_mfma_f32_16x16x32_bf16 v[116:119], v[182:185], v[200:203], 0
	v_mfma_f32_16x16x32_bf16 v[108:111], v[174:177], v[208:211], 0
	v_mfma_f32_16x16x32_bf16 v[100:103], v[182:185], v[208:211], 0
	v_mfma_f32_16x16x32_bf16 v[92:95], v[174:177], v[216:219], 0
	v_mfma_f32_16x16x32_bf16 v[84:87], v[182:185], v[216:219], 0
	v_mfma_f32_16x16x32_bf16 v[76:79], v[174:177], v[224:227], 0
	v_mfma_f32_16x16x32_bf16 v[68:71], v[182:185], v[224:227], 0
	v_mfma_f32_16x16x32_bf16 v[124:127], v[178:181], v[204:207], v[124:127]
	v_mfma_f32_16x16x32_bf16 v[116:119], v[186:189], v[204:207], v[116:119]
	v_mfma_f32_16x16x32_bf16 v[108:111], v[178:181], v[212:215], v[108:111]
	v_mfma_f32_16x16x32_bf16 v[100:103], v[186:189], v[212:215], v[100:103]
	v_mfma_f32_16x16x32_bf16 v[92:95], v[178:181], v[220:223], v[92:95]
	v_mfma_f32_16x16x32_bf16 v[84:87], v[186:189], v[220:223], v[84:87]
	v_mfma_f32_16x16x32_bf16 v[76:79], v[178:181], v[228:231], v[76:79]
	v_mfma_f32_16x16x32_bf16 v[68:71], v[186:189], v[228:231], v[68:71]
	s_barrier
	s_add_i32 s33, s82, s20
	v_lshl_add_u64 v[146:147], s[70:71], 0, v[134:135]
	s_mov_b32 m0, s33
	ds_read_b128 v[200:203], v151 offset:16384
	ds_read_b128 v[204:207], v151 offset:17408
	ds_read_b128 v[208:211], v151 offset:18432
	ds_read_b128 v[212:215], v151 offset:19456
	ds_read_b128 v[216:219], v151 offset:20480
	ds_read_b128 v[220:223], v151 offset:21504
	ds_read_b128 v[224:227], v151 offset:22528
	ds_read_b128 v[228:231], v151 offset:23552
	global_load_lds_dwordx4 v[146:147], off
	s_add_i32 m0, s33, 0x2000
	s_add_u32 s82, s70, 0x40000
	v_lshl_add_u64 v[164:165], s[70:71], 0, v[138:139]
	s_addc_u32 s83, s71, 0
	s_add_i32 s6, s6, s20
	global_load_lds_dwordx4 v[164:165], off
	v_lshl_add_u64 v[232:233], s[82:83], 0, v[134:135]
	s_mov_b32 m0, s6
	v_lshl_add_u64 v[234:235], s[72:73], 0, v[136:137]
	global_load_lds_dwordx4 v[232:233], off
	v_lshl_add_u64 v[232:233], s[82:83], 0, v[138:139]
	s_add_i32 m0, s6, 0x2000
	s_nop 0
	global_load_lds_dwordx4 v[232:233], off
	v_lshl_add_u64 v[232:233], s[72:73], 0, v[132:133]
	s_mov_b32 m0, s35
	s_nop 0
	global_load_lds_dwordx4 v[232:233], off
	s_mov_b32 m0, s54
	s_nop 0
	global_load_lds_dwordx4 v[234:235], off
	s_waitcnt vmcnt(8)
	s_waitcnt lgkmcnt(0)
	s_barrier
	s_waitcnt lgkmcnt(0)
	v_mfma_f32_16x16x32_bf16 v[64:67], v[152:155], v[200:203], 0
	v_mfma_f32_16x16x32_bf16 v[56:59], v[160:163], v[200:203], 0
	v_mfma_f32_16x16x32_bf16 v[48:51], v[152:155], v[208:211], 0
	v_mfma_f32_16x16x32_bf16 v[40:43], v[160:163], v[208:211], 0
	v_mfma_f32_16x16x32_bf16 v[32:35], v[152:155], v[216:219], 0
	v_mfma_f32_16x16x32_bf16 v[24:27], v[160:163], v[216:219], 0
	v_mfma_f32_16x16x32_bf16 v[16:19], v[152:155], v[224:227], 0
	v_mfma_f32_16x16x32_bf16 v[8:11], v[160:163], v[224:227], 0
	v_mfma_f32_16x16x32_bf16 v[64:67], v[156:159], v[204:207], v[64:67]
	v_mfma_f32_16x16x32_bf16 v[56:59], v[168:171], v[204:207], v[56:59]
	v_mfma_f32_16x16x32_bf16 v[48:51], v[156:159], v[212:215], v[48:51]
	v_mfma_f32_16x16x32_bf16 v[40:43], v[168:171], v[212:215], v[40:43]
	v_mfma_f32_16x16x32_bf16 v[32:35], v[156:159], v[220:223], v[32:35]
	v_mfma_f32_16x16x32_bf16 v[24:27], v[168:171], v[220:223], v[24:27]
	v_mfma_f32_16x16x32_bf16 v[16:19], v[156:159], v[228:231], v[16:19]
	v_mfma_f32_16x16x32_bf16 v[8:11], v[168:171], v[228:231], v[8:11]
	v_mfma_f32_16x16x32_bf16 v[60:63], v[174:177], v[200:203], 0
	v_mfma_f32_16x16x32_bf16 v[52:55], v[182:185], v[200:203], 0
	v_mfma_f32_16x16x32_bf16 v[44:47], v[174:177], v[208:211], 0
	v_mfma_f32_16x16x32_bf16 v[36:39], v[182:185], v[208:211], 0
	v_mfma_f32_16x16x32_bf16 v[28:31], v[174:177], v[216:219], 0
	v_mfma_f32_16x16x32_bf16 v[20:23], v[182:185], v[216:219], 0
	v_mfma_f32_16x16x32_bf16 v[12:15], v[174:177], v[224:227], 0
	v_mfma_f32_16x16x32_bf16 v[4:7], v[182:185], v[224:227], 0
	v_mfma_f32_16x16x32_bf16 v[60:63], v[178:181], v[204:207], v[60:63]
	v_mfma_f32_16x16x32_bf16 v[52:55], v[186:189], v[204:207], v[52:55]
	v_mfma_f32_16x16x32_bf16 v[44:47], v[178:181], v[212:215], v[44:47]
	v_mfma_f32_16x16x32_bf16 v[36:39], v[186:189], v[212:215], v[36:39]
	v_mfma_f32_16x16x32_bf16 v[28:31], v[178:181], v[220:223], v[28:31]
	v_mfma_f32_16x16x32_bf16 v[20:23], v[186:189], v[220:223], v[20:23]
	v_mfma_f32_16x16x32_bf16 v[12:15], v[178:181], v[228:231], v[12:15]
	v_mfma_f32_16x16x32_bf16 v[4:7], v[186:189], v[228:231], v[4:7]
	s_barrier
	s_add_i32 s6, 0, 0x18000
	v_add_u32_e32 v2, s6, v148
	s_add_i32 s33, 0, 0x1c000
	ds_read_b128 v[152:155], v2
	ds_read_b128 v[156:159], v2 offset:1024
	ds_read_b128 v[160:163], v2 offset:2048
	ds_read_b128 v[168:171], v2 offset:3072
	v_add_u32_e32 v2, s33, v148
	ds_read_b128 v[174:177], v2
	ds_read_b128 v[178:181], v2 offset:1024
	ds_read_b128 v[182:185], v2 offset:2048
	ds_read_b128 v[186:189], v2 offset:3072
	s_add_u32 s72, s72, 0x40000
	s_addc_u32 s73, s73, 0
	s_mov_b32 m0, s55
	v_lshl_add_u64 v[236:237], s[72:73], 0, v[132:133]
	ds_read_b128 v[200:203], v151 offset:32768
	ds_read_b128 v[204:207], v151 offset:33792
	ds_read_b128 v[208:211], v151 offset:34816
	ds_read_b128 v[212:215], v151 offset:35840
	ds_read_b128 v[216:219], v151 offset:36864
	ds_read_b128 v[220:223], v151 offset:37888
	ds_read_b128 v[224:227], v151 offset:38912
	ds_read_b128 v[228:231], v151 offset:39936
	global_load_lds_dwordx4 v[236:237], off
	v_lshl_add_u64 v[236:237], s[72:73], 0, v[136:137]
	s_mov_b32 m0, s56
	s_nop 0
	global_load_lds_dwordx4 v[236:237], off
	s_waitcnt vmcnt(8)
	s_waitcnt lgkmcnt(0)
	s_barrier
	s_waitcnt lgkmcnt(0)
	v_mfma_f32_16x16x32_bf16 v[128:131], v[152:155], v[200:203], v[128:131]
	v_mfma_f32_16x16x32_bf16 v[120:123], v[160:163], v[200:203], v[120:123]
	v_mfma_f32_16x16x32_bf16 v[112:115], v[152:155], v[208:211], v[112:115]
	v_mfma_f32_16x16x32_bf16 v[104:107], v[160:163], v[208:211], v[104:107]
	v_mfma_f32_16x16x32_bf16 v[96:99], v[152:155], v[216:219], v[96:99]
	v_mfma_f32_16x16x32_bf16 v[88:91], v[160:163], v[216:219], v[88:91]
	v_mfma_f32_16x16x32_bf16 v[80:83], v[152:155], v[224:227], v[80:83]
	v_mfma_f32_16x16x32_bf16 v[72:75], v[160:163], v[224:227], v[72:75]
	v_mfma_f32_16x16x32_bf16 v[128:131], v[156:159], v[204:207], v[128:131]
	v_mfma_f32_16x16x32_bf16 v[120:123], v[168:171], v[204:207], v[120:123]
	v_mfma_f32_16x16x32_bf16 v[112:115], v[156:159], v[212:215], v[112:115]
	v_mfma_f32_16x16x32_bf16 v[104:107], v[168:171], v[212:215], v[104:107]
	v_mfma_f32_16x16x32_bf16 v[96:99], v[156:159], v[220:223], v[96:99]
	v_mfma_f32_16x16x32_bf16 v[88:91], v[168:171], v[220:223], v[88:91]
	v_mfma_f32_16x16x32_bf16 v[80:83], v[156:159], v[228:231], v[80:83]
	v_mfma_f32_16x16x32_bf16 v[72:75], v[168:171], v[228:231], v[72:75]
	v_mfma_f32_16x16x32_bf16 v[124:127], v[174:177], v[200:203], v[124:127]
	v_mfma_f32_16x16x32_bf16 v[116:119], v[182:185], v[200:203], v[116:119]
	v_mfma_f32_16x16x32_bf16 v[108:111], v[174:177], v[208:211], v[108:111]
	v_mfma_f32_16x16x32_bf16 v[100:103], v[182:185], v[208:211], v[100:103]
	v_mfma_f32_16x16x32_bf16 v[92:95], v[174:177], v[216:219], v[92:95]
	v_mfma_f32_16x16x32_bf16 v[84:87], v[182:185], v[216:219], v[84:87]
	v_mfma_f32_16x16x32_bf16 v[76:79], v[174:177], v[224:227], v[76:79]
	v_mfma_f32_16x16x32_bf16 v[68:71], v[182:185], v[224:227], v[68:71]
	v_mfma_f32_16x16x32_bf16 v[124:127], v[178:181], v[204:207], v[124:127]
	v_mfma_f32_16x16x32_bf16 v[116:119], v[186:189], v[204:207], v[116:119]
	v_mfma_f32_16x16x32_bf16 v[108:111], v[178:181], v[212:215], v[108:111]
	v_mfma_f32_16x16x32_bf16 v[100:103], v[186:189], v[212:215], v[100:103]
	v_mfma_f32_16x16x32_bf16 v[92:95], v[178:181], v[220:223], v[92:95]
	v_mfma_f32_16x16x32_bf16 v[84:87], v[186:189], v[220:223], v[84:87]
	v_mfma_f32_16x16x32_bf16 v[76:79], v[178:181], v[228:231], v[76:79]
	v_mfma_f32_16x16x32_bf16 v[68:71], v[186:189], v[228:231], v[68:71]
	s_barrier
	s_add_i32 s6, s6, s20
	v_lshl_add_u64 v[146:147], v[146:147], 0, s[30:31]
	s_mov_b32 m0, s6
	ds_read_b128 v[200:203], v151 offset:49152
	ds_read_b128 v[204:207], v151 offset:50176
	ds_read_b128 v[208:211], v151 offset:51200
	ds_read_b128 v[212:215], v151 offset:52224
	ds_read_b128 v[216:219], v151 offset:53248
	ds_read_b128 v[220:223], v151 offset:54272
	ds_read_b128 v[224:227], v151 offset:55296
	ds_read_b128 v[228:231], v151 offset:56320
	global_load_lds_dwordx4 v[146:147], off
	s_add_i32 m0, s6, 0x2000
	s_add_u32 s70, s70, 0x40080
	v_lshl_add_u64 v[146:147], v[164:165], 0, s[30:31]
	s_addc_u32 s71, s71, 0
	s_add_i32 s6, s33, s20
	global_load_lds_dwordx4 v[146:147], off
	v_lshl_add_u64 v[146:147], s[70:71], 0, v[134:135]
	s_mov_b32 m0, s6
	s_nop 0
	global_load_lds_dwordx4 v[146:147], off
	v_lshl_add_u64 v[146:147], s[70:71], 0, v[138:139]
	s_add_i32 m0, s6, 0x2000
	s_nop 0
	global_load_lds_dwordx4 v[146:147], off
	v_lshl_add_u64 v[146:147], v[232:233], 0, s[30:31]
	s_mov_b32 m0, s76
	s_nop 0
	global_load_lds_dwordx4 v[146:147], off
	v_lshl_add_u64 v[146:147], v[234:235], 0, s[30:31]
	s_mov_b32 m0, s77
	s_nop 0
	global_load_lds_dwordx4 v[146:147], off
	s_waitcnt vmcnt(8)
	s_waitcnt lgkmcnt(0)
.Lrot4_R:
	s_barrier
	s_waitcnt lgkmcnt(0)
	v_mfma_f32_16x16x32_bf16 v[64:67], v[152:155], v[200:203], v[64:67]
	v_mfma_f32_16x16x32_bf16 v[56:59], v[160:163], v[200:203], v[56:59]
	v_mfma_f32_16x16x32_bf16 v[48:51], v[152:155], v[208:211], v[48:51]
	v_mfma_f32_16x16x32_bf16 v[40:43], v[160:163], v[208:211], v[40:43]
	v_mfma_f32_16x16x32_bf16 v[32:35], v[152:155], v[216:219], v[32:35]
	v_mfma_f32_16x16x32_bf16 v[24:27], v[160:163], v[216:219], v[24:27]
	v_mfma_f32_16x16x32_bf16 v[16:19], v[152:155], v[224:227], v[16:19]
	v_mfma_f32_16x16x32_bf16 v[8:11], v[160:163], v[224:227], v[8:11]
	v_mfma_f32_16x16x32_bf16 v[64:67], v[156:159], v[204:207], v[64:67]
	v_mfma_f32_16x16x32_bf16 v[56:59], v[168:171], v[204:207], v[56:59]
	v_mfma_f32_16x16x32_bf16 v[48:51], v[156:159], v[212:215], v[48:51]
	v_mfma_f32_16x16x32_bf16 v[40:43], v[168:171], v[212:215], v[40:43]
	v_mfma_f32_16x16x32_bf16 v[32:35], v[156:159], v[220:223], v[32:35]
	v_mfma_f32_16x16x32_bf16 v[24:27], v[168:171], v[220:223], v[24:27]
	v_mfma_f32_16x16x32_bf16 v[16:19], v[156:159], v[228:231], v[16:19]
	v_mfma_f32_16x16x32_bf16 v[8:11], v[168:171], v[228:231], v[8:11]
	v_mfma_f32_16x16x32_bf16 v[60:63], v[174:177], v[200:203], v[60:63]
	v_mfma_f32_16x16x32_bf16 v[52:55], v[182:185], v[200:203], v[52:55]
	v_mfma_f32_16x16x32_bf16 v[44:47], v[174:177], v[208:211], v[44:47]
	v_mfma_f32_16x16x32_bf16 v[36:39], v[182:185], v[208:211], v[36:39]
	v_mfma_f32_16x16x32_bf16 v[28:31], v[174:177], v[216:219], v[28:31]
	v_mfma_f32_16x16x32_bf16 v[20:23], v[182:185], v[216:219], v[20:23]
	v_mfma_f32_16x16x32_bf16 v[12:15], v[174:177], v[224:227], v[12:15]
	v_mfma_f32_16x16x32_bf16 v[4:7], v[182:185], v[224:227], v[4:7]
	v_mfma_f32_16x16x32_bf16 v[60:63], v[178:181], v[204:207], v[60:63]
	v_mfma_f32_16x16x32_bf16 v[52:55], v[186:189], v[204:207], v[52:55]
	v_mfma_f32_16x16x32_bf16 v[44:47], v[178:181], v[212:215], v[44:47]
	v_mfma_f32_16x16x32_bf16 v[36:39], v[186:189], v[212:215], v[36:39]
	v_mfma_f32_16x16x32_bf16 v[28:31], v[178:181], v[220:223], v[28:31]
	v_mfma_f32_16x16x32_bf16 v[20:23], v[186:189], v[220:223], v[20:23]
	v_mfma_f32_16x16x32_bf16 v[12:15], v[178:181], v[228:231], v[12:15]
	v_mfma_f32_16x16x32_bf16 v[4:7], v[186:189], v[228:231], v[4:7]
	s_barrier
	s_add_i32 s80, s80, 2
	s_add_u32 s68, s68, 0x100
	s_addc_u32 s69, s69, 0
	s_add_u32 s61, s61, 0x100
	s_addc_u32 s67, s67, 0
	s_cmp_gt_u32 s80, 13
	s_cbranch_scc1 .Lrot4_X
.LBB0_664:
	s_add_u32 s6, s68, 0xfffc0080
	s_addc_u32 s33, s69, -1
	s_add_i32 s82, 0, 0x10000
	s_cmp_eq_u32 s80, 12
	s_cselect_b32 s73, s10, s33
	s_cselect_b32 s72, s11, s6
	v_add_u32_e32 v2, s82, v148
	s_cselect_b32 s71, s15, s67
	s_cselect_b32 s70, s59, s61
	s_add_i32 s6, 0, 0x14000
	ds_read_b128 v[152:155], v2
	ds_read_b128 v[156:159], v2 offset:1024
	ds_read_b128 v[160:163], v2 offset:2048
	ds_read_b128 v[168:171], v2 offset:3072
	v_add_u32_e32 v2, s6, v148
	ds_read_b128 v[174:177], v2
	ds_read_b128 v[178:181], v2 offset:1024
	ds_read_b128 v[182:185], v2 offset:2048
	ds_read_b128 v[186:189], v2 offset:3072
	v_lshl_add_u64 v[146:147], s[68:69], 0, v[142:143]
	s_add_i32 m0, s35, 0xc000
	ds_read_b128 v[200:203], v151
	ds_read_b128 v[204:207], v151 offset:1024
	ds_read_b128 v[208:211], v151 offset:2048
	ds_read_b128 v[212:215], v151 offset:3072
	ds_read_b128 v[216:219], v151 offset:4096
	ds_read_b128 v[220:223], v151 offset:5120
	ds_read_b128 v[224:227], v151 offset:6144
	ds_read_b128 v[228:231], v151 offset:7168
	global_load_lds_dwordx4 v[146:147], off
	v_lshl_add_u64 v[146:147], s[68:69], 0, v[144:145]
	s_add_i32 m0, s35, 0xe000
	s_nop 0
	global_load_lds_dwordx4 v[146:147], off
	s_waitcnt vmcnt(8)
	s_waitcnt lgkmcnt(0)
	s_barrier
	s_waitcnt lgkmcnt(0)
	v_mfma_f32_16x16x32_bf16 v[128:131], v[152:155], v[200:203], v[128:131]
	v_mfma_f32_16x16x32_bf16 v[120:123], v[160:163], v[200:203], v[120:123]
	v_mfma_f32_16x16x32_bf16 v[112:115], v[152:155], v[208:211], v[112:115]
	v_mfma_f32_16x16x32_bf16 v[104:107], v[160:163], v[208:211], v[104:107]
	v_mfma_f32_16x16x32_bf16 v[96:99], v[152:155], v[216:219], v[96:99]
	v_mfma_f32_16x16x32_bf16 v[88:91], v[160:163], v[216:219], v[88:91]
	v_mfma_f32_16x16x32_bf16 v[80:83], v[152:155], v[224:227], v[80:83]
	v_mfma_f32_16x16x32_bf16 v[72:75], v[160:163], v[224:227], v[72:75]
	v_mfma_f32_16x16x32_bf16 v[128:131], v[156:159], v[204:207], v[128:131]
	v_mfma_f32_16x16x32_bf16 v[120:123], v[168:171], v[204:207], v[120:123]
	v_mfma_f32_16x16x32_bf16 v[112:115], v[156:159], v[212:215], v[112:115]
	v_mfma_f32_16x16x32_bf16 v[104:107], v[168:171], v[212:215], v[104:107]
	v_mfma_f32_16x16x32_bf16 v[96:99], v[156:159], v[220:223], v[96:99]
	v_mfma_f32_16x16x32_bf16 v[88:91], v[168:171], v[220:223], v[88:91]
	v_mfma_f32_16x16x32_bf16 v[80:83], v[156:159], v[228:231], v[80:83]
	v_mfma_f32_16x16x32_bf16 v[72:75], v[168:171], v[228:231], v[72:75]
	v_mfma_f32_16x16x32_bf16 v[124:127], v[174:177], v[200:203], v[124:127]
	v_mfma_f32_16x16x32_bf16 v[116:119], v[182:185], v[200:203], v[116:119]
	v_mfma_f32_16x16x32_bf16 v[108:111], v[174:177], v[208:211], v[108:111]
	v_mfma_f32_16x16x32_bf16 v[100:103], v[182:185], v[208:211], v[100:103]
	v_mfma_f32_16x16x32_bf16 v[92:95], v[174:177], v[216:219], v[92:95]
	v_mfma_f32_16x16x32_bf16 v[84:87], v[182:185], v[216:219], v[84:87]
	v_mfma_f32_16x16x32_bf16 v[76:79], v[174:177], v[224:227], v[76:79]
	v_mfma_f32_16x16x32_bf16 v[68:71], v[182:185], v[224:227], v[68:71]
	v_mfma_f32_16x16x32_bf16 v[124:127], v[178:181], v[204:207], v[124:127]
	v_mfma_f32_16x16x32_bf16 v[116:119], v[186:189], v[204:207], v[116:119]
	v_mfma_f32_16x16x32_bf16 v[108:111], v[178:181], v[212:215], v[108:111]
	v_mfma_f32_16x16x32_bf16 v[100:103], v[186:189], v[212:215], v[100:103]
	v_mfma_f32_16x16x32_bf16 v[92:95], v[178:181], v[220:223], v[92:95]
	v_mfma_f32_16x16x32_bf16 v[84:87], v[186:189], v[220:223], v[84:87]
	v_mfma_f32_16x16x32_bf16 v[76:79], v[178:181], v[228:231], v[76:79]
	v_mfma_f32_16x16x32_bf16 v[68:71], v[186:189], v[228:231], v[68:71]
	s_barrier
	s_add_i32 s33, s82, s20
	v_lshl_add_u64 v[146:147], s[70:71], 0, v[134:135]
	s_mov_b32 m0, s33
	ds_read_b128 v[200:203], v151 offset:16384
	ds_read_b128 v[204:207], v151 offset:17408
	ds_read_b128 v[208:211], v151 offset:18432
	ds_read_b128 v[212:215], v151 offset:19456
	ds_read_b128 v[216:219], v151 offset:20480
	ds_read_b128 v[220:223], v151 offset:21504
	ds_read_b128 v[224:227], v151 offset:22528
	ds_read_b128 v[228:231], v151 offset:23552
	global_load_lds_dwordx4 v[146:147], off
	s_add_i32 m0, s33, 0x2000
	s_add_u32 s82, s70, 0x40000
	v_lshl_add_u64 v[164:165], s[70:71], 0, v[138:139]
	s_addc_u32 s83, s71, 0
	s_add_i32 s6, s6, s20
	global_load_lds_dwordx4 v[164:165], off
	v_lshl_add_u64 v[232:233], s[82:83], 0, v[134:135]
	s_mov_b32 m0, s6
	v_lshl_add_u64 v[234:235], s[72:73], 0, v[136:137]
	global_load_lds_dwordx4 v[232:233], off
	v_lshl_add_u64 v[232:233], s[82:83], 0, v[138:139]
	s_add_i32 m0, s6, 0x2000
	s_nop 0
	global_load_lds_dwordx4 v[232:233], off
	v_lshl_add_u64 v[232:233], s[72:73], 0, v[132:133]
	s_mov_b32 m0, s35
	s_nop 0
	global_load_lds_dwordx4 v[232:233], off
	s_mov_b32 m0, s54
	s_nop 0
	global_load_lds_dwordx4 v[234:235], off
	s_waitcnt vmcnt(8)
	s_waitcnt lgkmcnt(0)
	s_barrier
	s_waitcnt lgkmcnt(0)
	v_mfma_f32_16x16x32_bf16 v[64:67], v[152:155], v[200:203], v[64:67]
	v_mfma_f32_16x16x32_bf16 v[56:59], v[160:163], v[200:203], v[56:59]
	v_mfma_f32_16x16x32_bf16 v[48:51], v[152:155], v[208:211], v[48:51]
	v_mfma_f32_16x16x32_bf16 v[40:43], v[160:163], v[208:211], v[40:43]
	v_mfma_f32_16x16x32_bf16 v[32:35], v[152:155], v[216:219], v[32:35]
	v_mfma_f32_16x16x32_bf16 v[24:27], v[160:163], v[216:219], v[24:27]
	v_mfma_f32_16x16x32_bf16 v[16:19], v[152:155], v[224:227], v[16:19]
	v_mfma_f32_16x16x32_bf16 v[8:11], v[160:163], v[224:227], v[8:11]
	v_mfma_f32_16x16x32_bf16 v[64:67], v[156:159], v[204:207], v[64:67]
	v_mfma_f32_16x16x32_bf16 v[56:59], v[168:171], v[204:207], v[56:59]
	v_mfma_f32_16x16x32_bf16 v[48:51], v[156:159], v[212:215], v[48:51]
	v_mfma_f32_16x16x32_bf16 v[40:43], v[168:171], v[212:215], v[40:43]
	v_mfma_f32_16x16x32_bf16 v[32:35], v[156:159], v[220:223], v[32:35]
	v_mfma_f32_16x16x32_bf16 v[24:27], v[168:171], v[220:223], v[24:27]
	v_mfma_f32_16x16x32_bf16 v[16:19], v[156:159], v[228:231], v[16:19]
	v_mfma_f32_16x16x32_bf16 v[8:11], v[168:171], v[228:231], v[8:11]
	v_mfma_f32_16x16x32_bf16 v[60:63], v[174:177], v[200:203], v[60:63]
	v_mfma_f32_16x16x32_bf16 v[52:55], v[182:185], v[200:203], v[52:55]
	v_mfma_f32_16x16x32_bf16 v[44:47], v[174:177], v[208:211], v[44:47]
	v_mfma_f32_16x16x32_bf16 v[36:39], v[182:185], v[208:211], v[36:39]
	v_mfma_f32_16x16x32_bf16 v[28:31], v[174:177], v[216:219], v[28:31]
	v_mfma_f32_16x16x32_bf16 v[20:23], v[182:185], v[216:219], v[20:23]
	v_mfma_f32_16x16x32_bf16 v[12:15], v[174:177], v[224:227], v[12:15]
	v_mfma_f32_16x16x32_bf16 v[4:7], v[182:185], v[224:227], v[4:7]
	v_mfma_f32_16x16x32_bf16 v[60:63], v[178:181], v[204:207], v[60:63]
	v_mfma_f32_16x16x32_bf16 v[52:55], v[186:189], v[204:207], v[52:55]
	v_mfma_f32_16x16x32_bf16 v[44:47], v[178:181], v[212:215], v[44:47]
	v_mfma_f32_16x16x32_bf16 v[36:39], v[186:189], v[212:215], v[36:39]
	v_mfma_f32_16x16x32_bf16 v[28:31], v[178:181], v[220:223], v[28:31]
	v_mfma_f32_16x16x32_bf16 v[20:23], v[186:189], v[220:223], v[20:23]
	v_mfma_f32_16x16x32_bf16 v[12:15], v[178:181], v[228:231], v[12:15]
	v_mfma_f32_16x16x32_bf16 v[4:7], v[186:189], v[228:231], v[4:7]
	s_barrier
	s_add_i32 s6, 0, 0x18000
	v_add_u32_e32 v2, s6, v148
	s_add_i32 s33, 0, 0x1c000
	ds_read_b128 v[152:155], v2
	ds_read_b128 v[156:159], v2 offset:1024
	ds_read_b128 v[160:163], v2 offset:2048
	ds_read_b128 v[168:171], v2 offset:3072
	v_add_u32_e32 v2, s33, v148
	ds_read_b128 v[174:177], v2
	ds_read_b128 v[178:181], v2 offset:1024
	ds_read_b128 v[182:185], v2 offset:2048
	ds_read_b128 v[186:189], v2 offset:3072
	s_add_u32 s72, s72, 0x40000
	s_addc_u32 s73, s73, 0
	s_mov_b32 m0, s55
	v_lshl_add_u64 v[236:237], s[72:73], 0, v[132:133]
	ds_read_b128 v[200:203], v151 offset:32768
	ds_read_b128 v[204:207], v151 offset:33792
	ds_read_b128 v[208:211], v151 offset:34816
	ds_read_b128 v[212:215], v151 offset:35840
	ds_read_b128 v[216:219], v151 offset:36864
	ds_read_b128 v[220:223], v151 offset:37888
	ds_read_b128 v[224:227], v151 offset:38912
	ds_read_b128 v[228:231], v151 offset:39936
	global_load_lds_dwordx4 v[236:237], off
	v_lshl_add_u64 v[236:237], s[72:73], 0, v[136:137]
	s_mov_b32 m0, s56
	s_nop 0
	global_load_lds_dwordx4 v[236:237], off
	s_waitcnt vmcnt(8)
	s_waitcnt lgkmcnt(0)
	s_barrier
	s_waitcnt lgkmcnt(0)
	v_mfma_f32_16x16x32_bf16 v[128:131], v[152:155], v[200:203], v[128:131]
	v_mfma_f32_16x16x32_bf16 v[120:123], v[160:163], v[200:203], v[120:123]
	v_mfma_f32_16x16x32_bf16 v[112:115], v[152:155], v[208:211], v[112:115]
	v_mfma_f32_16x16x32_bf16 v[104:107], v[160:163], v[208:211], v[104:107]
	v_mfma_f32_16x16x32_bf16 v[96:99], v[152:155], v[216:219], v[96:99]
	v_mfma_f32_16x16x32_bf16 v[88:91], v[160:163], v[216:219], v[88:91]
	v_mfma_f32_16x16x32_bf16 v[80:83], v[152:155], v[224:227], v[80:83]
	v_mfma_f32_16x16x32_bf16 v[72:75], v[160:163], v[224:227], v[72:75]
	v_mfma_f32_16x16x32_bf16 v[128:131], v[156:159], v[204:207], v[128:131]
	v_mfma_f32_16x16x32_bf16 v[120:123], v[168:171], v[204:207], v[120:123]
	v_mfma_f32_16x16x32_bf16 v[112:115], v[156:159], v[212:215], v[112:115]
	v_mfma_f32_16x16x32_bf16 v[104:107], v[168:171], v[212:215], v[104:107]
	v_mfma_f32_16x16x32_bf16 v[96:99], v[156:159], v[220:223], v[96:99]
	v_mfma_f32_16x16x32_bf16 v[88:91], v[168:171], v[220:223], v[88:91]
	v_mfma_f32_16x16x32_bf16 v[80:83], v[156:159], v[228:231], v[80:83]
	v_mfma_f32_16x16x32_bf16 v[72:75], v[168:171], v[228:231], v[72:75]
	v_mfma_f32_16x16x32_bf16 v[124:127], v[174:177], v[200:203], v[124:127]
	v_mfma_f32_16x16x32_bf16 v[116:119], v[182:185], v[200:203], v[116:119]
	v_mfma_f32_16x16x32_bf16 v[108:111], v[174:177], v[208:211], v[108:111]
	v_mfma_f32_16x16x32_bf16 v[100:103], v[182:185], v[208:211], v[100:103]
	v_mfma_f32_16x16x32_bf16 v[92:95], v[174:177], v[216:219], v[92:95]
	v_mfma_f32_16x16x32_bf16 v[84:87], v[182:185], v[216:219], v[84:87]
	v_mfma_f32_16x16x32_bf16 v[76:79], v[174:177], v[224:227], v[76:79]
	v_mfma_f32_16x16x32_bf16 v[68:71], v[182:185], v[224:227], v[68:71]
	v_mfma_f32_16x16x32_bf16 v[124:127], v[178:181], v[204:207], v[124:127]
	v_mfma_f32_16x16x32_bf16 v[116:119], v[186:189], v[204:207], v[116:119]
	v_mfma_f32_16x16x32_bf16 v[108:111], v[178:181], v[212:215], v[108:111]
	v_mfma_f32_16x16x32_bf16 v[100:103], v[186:189], v[212:215], v[100:103]
	v_mfma_f32_16x16x32_bf16 v[92:95], v[178:181], v[220:223], v[92:95]
	v_mfma_f32_16x16x32_bf16 v[84:87], v[186:189], v[220:223], v[84:87]
	v_mfma_f32_16x16x32_bf16 v[76:79], v[178:181], v[228:231], v[76:79]
	v_mfma_f32_16x16x32_bf16 v[68:71], v[186:189], v[228:231], v[68:71]
	s_barrier
	s_add_i32 s6, s6, s20
	v_lshl_add_u64 v[146:147], v[146:147], 0, s[30:31]
	s_mov_b32 m0, s6
	ds_read_b128 v[200:203], v151 offset:49152
	ds_read_b128 v[204:207], v151 offset:50176
	ds_read_b128 v[208:211], v151 offset:51200
	ds_read_b128 v[212:215], v151 offset:52224
	ds_read_b128 v[216:219], v151 offset:53248
	ds_read_b128 v[220:223], v151 offset:54272
	ds_read_b128 v[224:227], v151 offset:55296
	ds_read_b128 v[228:231], v151 offset:56320
	global_load_lds_dwordx4 v[146:147], off
	s_add_i32 m0, s6, 0x2000
	s_add_u32 s70, s70, 0x40080
	v_lshl_add_u64 v[146:147], v[164:165], 0, s[30:31]
	s_addc_u32 s71, s71, 0
	s_add_i32 s6, s33, s20
	global_load_lds_dwordx4 v[146:147], off
	v_lshl_add_u64 v[146:147], s[70:71], 0, v[134:135]
	s_mov_b32 m0, s6
	s_nop 0
	global_load_lds_dwordx4 v[146:147], off
	v_lshl_add_u64 v[146:147], s[70:71], 0, v[138:139]
	s_add_i32 m0, s6, 0x2000
	s_nop 0
	global_load_lds_dwordx4 v[146:147], off
	v_lshl_add_u64 v[146:147], v[232:233], 0, s[30:31]
	s_mov_b32 m0, s76
	s_nop 0
	global_load_lds_dwordx4 v[146:147], off
	v_lshl_add_u64 v[146:147], v[234:235], 0, s[30:31]
	s_mov_b32 m0, s77
	s_nop 0
	global_load_lds_dwordx4 v[146:147], off
	s_waitcnt vmcnt(8)
	s_waitcnt lgkmcnt(0)
	s_branch .Lrot4_R
